# FoX loop software pipelined: per iteration max/sub(T)+PV(T+1) then exp/sum/cvt(T)+QK(T-1); scores moved to a second register set by the subtraction; single barrier per iteration
# speedup vs baseline: 1.0089x; 1.0082x over previous
.LBB0_178:
	s_barrier
	s_cmp_lt_u32 s47, 3
	s_cbranch_scc1 .LBB0_180
	s_add_i32 s78, s44, s50
	s_lshl_b64 s[38:39], s[78:79], s41
	s_and_b32 s37, s49, 0xc000
	v_lshl_add_u64 v[196:197], s[38:39], 1, v[180:181]
	s_add_i32 s38, s45, s37
	s_mov_b32 s37, m0
	s_mov_b32 m0, s38
	s_nop 0
	global_load_lds_dwordx4 v[196:197], off
	s_mov_b32 m0, s37
	s_mov_b32 s37, s79
	v_lshl_add_u64 v[196:197], v[196:197], 0, s[36:37]
	s_addk_i32 s38, 0x2000
	s_mov_b32 s37, m0
	s_mov_b32 m0, s38
	s_nop 0
	global_load_lds_dwordx4 v[196:197], off
	s_mov_b32 m0, s37
.LBB0_180:
	s_cmp_gt_i32 s47, s46
	s_cbranch_scc1 .LBB0_188
	s_cmp_lg_u32 s46, s47
	s_cbranch_scc1 .Lfx_body
	v_add_u32_e32 v1, s48, v189
	ds_read_b128 v[126:129], v1 offset:32768
	ds_read_b128 v[106:109], v1 offset:40960
	ds_read_b128 v[98:101], v1 offset:33792
	ds_read_b128 v[102:105], v1 offset:41984
	ds_read_b128 v[86:89], v1 offset:34816
	ds_read_b128 v[94:97], v1 offset:43008
	ds_read_b128 v[82:85], v1 offset:35840
	ds_read_b128 v[90:93], v1 offset:44032
	ds_read_b128 v[34:37], v175
	ds_read_b128 v[38:41], v175 offset:16
	ds_read_b128 v[42:45], v175 offset:64
	ds_read_b128 v[46:49], v175 offset:80
	ds_read_b128 v[50:53], v175 offset:128
	ds_read_b128 v[54:57], v175 offset:144
	ds_read_b128 v[58:61], v175 offset:192
	ds_read_b128 v[62:65], v175 offset:208
	s_waitcnt lgkmcnt(0)
	v_mfma_f32_32x32x16_bf16 v[34:49], v[126:129], v[66:69], v[34:49]
	v_mfma_f32_32x32x16_bf16 v[50:65], v[106:109], v[66:69], v[50:65]
	v_mfma_f32_32x32x16_bf16 v[34:49], v[98:101], v[70:73], v[34:49]
	v_mfma_f32_32x32x16_bf16 v[50:65], v[102:105], v[70:73], v[50:65]
	v_mfma_f32_32x32x16_bf16 v[34:49], v[86:89], v[74:77], v[34:49]
	v_mfma_f32_32x32x16_bf16 v[50:65], v[94:97], v[74:77], v[50:65]
	v_mfma_f32_32x32x16_bf16 v[34:49], v[82:85], v[78:81], v[34:49]
	v_mfma_f32_32x32x16_bf16 v[50:65], v[90:93], v[78:81], v[50:65]
	s_nop 1
	v_add_u32_e32 v1, s50, v166
	v_add_u32_e32 v163, 0xe0, v1
	v_add_u32_e32 v162, 0xc0, v1
	v_cmp_le_i32_e32 vcc, v163, v186
	s_nop 6
	v_cndmask_b32_e32 v50, v239, v50, vcc
	v_cmp_lt_i32_e32 vcc, v162, v186
	s_nop 1
	v_cndmask_b32_e32 v35, v239, v35, vcc
	v_cmp_le_i32_e32 vcc, v162, v186
	v_add_u32_e32 v162, 0xe1, v1
	s_nop 0
	v_cndmask_b32_e32 v34, v239, v34, vcc
	v_cmp_le_i32_e32 vcc, v162, v186
	v_add_u32_e32 v162, 0xc2, v1
	s_nop 0
	v_cndmask_b32_e32 v51, v239, v51, vcc
	v_cmp_le_i32_e32 vcc, v162, v186
	v_add_u32_e32 v162, 0xe2, v1
	s_nop 0
	v_cndmask_b32_e32 v36, v239, v36, vcc
	v_cmp_le_i32_e32 vcc, v162, v186
	v_add_u32_e32 v162, 0xc3, v1
	s_nop 0
	v_cndmask_b32_e32 v52, v239, v52, vcc
	v_cmp_le_i32_e32 vcc, v162, v186
	v_add_u32_e32 v162, 0xe3, v1
	s_nop 0
	v_cndmask_b32_e32 v37, v239, v37, vcc
	v_cmp_le_i32_e32 vcc, v162, v186
	v_add_u32_e32 v162, 0xc4, v1
	s_nop 0
	v_cndmask_b32_e32 v53, v239, v53, vcc
	v_cmp_le_i32_e32 vcc, v162, v186
	v_add_u32_e32 v162, 0xe4, v1
	s_nop 0
	v_cndmask_b32_e32 v38, v239, v38, vcc
	v_cmp_le_i32_e32 vcc, v162, v186
	v_add_u32_e32 v162, 0xc5, v1
	s_nop 0
	v_cndmask_b32_e32 v54, v239, v54, vcc
	v_cmp_le_i32_e32 vcc, v162, v186
	v_add_u32_e32 v162, 0xe5, v1
	s_nop 0
	v_cndmask_b32_e32 v39, v239, v39, vcc
	v_cmp_le_i32_e32 vcc, v162, v186
	v_add_u32_e32 v162, 0xc6, v1
	s_nop 0
	v_cndmask_b32_e32 v55, v239, v55, vcc
	v_cmp_le_i32_e32 vcc, v162, v186
	v_add_u32_e32 v162, 0xe6, v1
	s_nop 0
	v_cndmask_b32_e32 v40, v239, v40, vcc
	v_cmp_le_i32_e32 vcc, v162, v186
	v_add_u32_e32 v162, 0xc7, v1
	s_nop 0
	v_cndmask_b32_e32 v56, v239, v56, vcc
	v_cmp_le_i32_e32 vcc, v162, v186
	v_add_u32_e32 v162, 0xe7, v1
	s_nop 0
	v_cndmask_b32_e32 v41, v239, v41, vcc
	v_cmp_le_i32_e32 vcc, v162, v186
	v_add_u32_e32 v162, 0xd0, v1
	s_nop 0
	v_cndmask_b32_e32 v57, v239, v57, vcc
	v_cmp_le_i32_e32 vcc, v162, v186
	v_add_u32_e32 v162, 0xf0, v1
	s_nop 0
	v_cndmask_b32_e32 v42, v239, v42, vcc
	v_cmp_le_i32_e32 vcc, v162, v186
	v_add_u32_e32 v162, 0xd1, v1
	s_nop 0
	v_cndmask_b32_e32 v58, v239, v58, vcc
	v_cmp_le_i32_e32 vcc, v162, v186
	v_add_u32_e32 v162, 0xf1, v1
	s_nop 0
	v_cndmask_b32_e32 v43, v239, v43, vcc
	v_cmp_le_i32_e32 vcc, v162, v186
	v_add_u32_e32 v162, 0xd2, v1
	s_nop 0
	v_cndmask_b32_e32 v59, v239, v59, vcc
	v_cmp_le_i32_e32 vcc, v162, v186
	v_add_u32_e32 v162, 0xf2, v1
	s_nop 0
	v_cndmask_b32_e32 v44, v239, v44, vcc
	v_cmp_le_i32_e32 vcc, v162, v186
	v_add_u32_e32 v162, 0xd3, v1
	s_nop 0
	v_cndmask_b32_e32 v60, v239, v60, vcc
	v_cmp_le_i32_e32 vcc, v162, v186
	v_add_u32_e32 v162, 0xf3, v1
	s_nop 0
	v_cndmask_b32_e32 v45, v239, v45, vcc
	v_cmp_le_i32_e32 vcc, v162, v186
	v_add_u32_e32 v162, 0xd4, v1
	s_nop 0
	v_cndmask_b32_e32 v61, v239, v61, vcc
	v_cmp_le_i32_e32 vcc, v162, v186
	v_add_u32_e32 v162, 0xf4, v1
	s_nop 0
	v_cndmask_b32_e32 v46, v239, v46, vcc
	v_cmp_le_i32_e32 vcc, v162, v186
	v_add_u32_e32 v162, 0xd5, v1
	s_nop 0
	v_cndmask_b32_e32 v62, v239, v62, vcc
	v_cmp_le_i32_e32 vcc, v162, v186
	v_add_u32_e32 v162, 0xf5, v1
	s_nop 0
	v_cndmask_b32_e32 v47, v239, v47, vcc
	v_cmp_le_i32_e32 vcc, v162, v186
	v_add_u32_e32 v162, 0xd6, v1
	s_nop 0
	v_cndmask_b32_e32 v63, v239, v63, vcc
	v_cmp_le_i32_e32 vcc, v162, v186
	v_add_u32_e32 v162, 0xf6, v1
	s_nop 0
	v_cndmask_b32_e32 v48, v239, v48, vcc
	v_cmp_le_i32_e32 vcc, v162, v186
	v_add_u32_e32 v162, 0xd7, v1
	v_add_u32_e32 v1, 0xf7, v1
	v_cndmask_b32_e32 v64, v239, v64, vcc
	v_cmp_le_i32_e32 vcc, v162, v186
	s_nop 1
	v_cndmask_b32_e32 v49, v239, v49, vcc
	v_cmp_le_i32_e32 vcc, v1, v186
	s_nop 1
	v_cndmask_b32_e32 v65, v239, v65, vcc
.Lfx_body:
	s_add_i32 s37, s49, 0x18000
	s_and_b32 s37, s37, 0xc000
	v_add_u32_e32 v1, s37, v189
	ds_read_b128 v[126:129], v1 offset:32768
	ds_read_b128 v[106:109], v1 offset:40960
	ds_read_b128 v[98:101], v1 offset:33792
	ds_read_b128 v[102:105], v1 offset:41984
	ds_read_b128 v[86:89], v1 offset:34816
	ds_read_b128 v[94:97], v1 offset:43008
	ds_read_b128 v[82:85], v1 offset:35840
	ds_read_b128 v[90:93], v1 offset:44032
	s_add_i32 s37, s49, 0xc000
	s_and_b32 s37, s37, 0xc000
	v_add_u32_e32 v194, s37, v189
	v_mfma_f32_32x32x16_bf16 v[18:33], v[158:161], v[122:125], v[18:33]
	v_max3_f32 v1, v34, v35, v36
	ds_read_b128 v[158:161], v194 offset:36864
	v_max3_f32 v162, v50, v51, v52
	v_max3_f32 v1, v1, v37, v38
	v_max3_f32 v162, v162, v53, v54
	v_max3_f32 v1, v1, v39, v40
	v_max3_f32 v162, v162, v55, v56
	v_mfma_f32_32x32x16_bf16 v[18:33], v[154:157], v[118:121], v[18:33]
	v_max3_f32 v1, v1, v41, v42
	ds_read_b128 v[154:157], v194 offset:37888
	v_max3_f32 v162, v162, v57, v58
	v_max3_f32 v1, v1, v43, v44
	v_max3_f32 v162, v162, v59, v60
	v_max3_f32 v1, v1, v45, v46
	v_max3_f32 v162, v162, v61, v62
	v_mfma_f32_32x32x16_bf16 v[2:17], v[142:145], v[122:125], v[2:17]
	v_max3_f32 v1, v1, v47, v48
	ds_read_b128 v[142:145], v194 offset:38912
	v_max3_f32 v162, v162, v63, v64
	v_max3_f32 v162, v162, v65, v49
	v_max_f32_e32 v1, v1, v162
	ds_bpermute_b32 v163, v203, v1
	v_mfma_f32_32x32x16_bf16 v[18:33], v[150:153], v[114:117], v[18:33]
	v_mfma_f32_32x32x16_bf16 v[2:17], v[138:141], v[118:121], v[2:17]
	s_waitcnt lgkmcnt(0)
	v_max3_f32 v1, v207, v1, v163
	ds_read_b128 v[150:153], v194 offset:45056
	ds_read_b128 v[138:141], v194 offset:39936
	v_sub_f32_e32 v164, v207, v1
	v_exp_f32_e32 v164, v164
	v_sub_f32_e32 v208, v34, v1
	v_sub_f32_e32 v209, v35, v1
	v_sub_f32_e32 v210, v36, v1
	v_sub_f32_e32 v211, v37, v1
	v_sub_f32_e32 v212, v38, v1
	v_sub_f32_e32 v213, v39, v1
	v_sub_f32_e32 v214, v40, v1
	v_sub_f32_e32 v215, v41, v1
	v_mfma_f32_32x32x16_bf16 v[18:33], v[146:149], v[110:113], v[18:33]
	v_sub_f32_e32 v216, v42, v1
	v_sub_f32_e32 v217, v43, v1
	v_sub_f32_e32 v218, v44, v1
	v_sub_f32_e32 v219, v45, v1
	v_sub_f32_e32 v220, v46, v1
	v_sub_f32_e32 v221, v47, v1
	v_sub_f32_e32 v222, v48, v1
	v_sub_f32_e32 v223, v49, v1
	ds_read_b128 v[146:149], v194 offset:46080
	v_mfma_f32_32x32x16_bf16 v[2:17], v[134:137], v[114:117], v[2:17]
	v_sub_f32_e32 v224, v50, v1
	v_sub_f32_e32 v225, v51, v1
	v_sub_f32_e32 v226, v52, v1
	v_sub_f32_e32 v227, v53, v1
	v_sub_f32_e32 v228, v54, v1
	v_sub_f32_e32 v229, v55, v1
	v_sub_f32_e32 v230, v56, v1
	v_sub_f32_e32 v231, v57, v1
	ds_read_b128 v[134:137], v194 offset:47104
	v_mfma_f32_32x32x16_bf16 v[2:17], v[130:133], v[110:113], v[2:17]
	v_sub_f32_e32 v244, v58, v1
	v_sub_f32_e32 v245, v59, v1
	v_sub_f32_e32 v246, v60, v1
	v_sub_f32_e32 v247, v61, v1
	v_sub_f32_e32 v248, v62, v1
	v_sub_f32_e32 v249, v63, v1
	v_sub_f32_e32 v250, v64, v1
	v_sub_f32_e32 v251, v65, v1
	ds_read_b128 v[130:133], v194 offset:48128
	v_add_u32_e32 v195, 0xffffff00, v175
	v_max_i32_e32 v195, v195, v0
	ds_read_b128 v[34:37], v195
	ds_read_b128 v[38:41], v195 offset:16
	ds_read_b128 v[42:45], v195 offset:64
	ds_read_b128 v[46:49], v195 offset:80
	ds_read_b128 v[50:53], v195 offset:128
	ds_read_b128 v[54:57], v195 offset:144
	ds_read_b128 v[58:61], v195 offset:192
	ds_read_b128 v[62:65], v195 offset:208
	v_exp_f32_e32 v208, v208
	v_exp_f32_e32 v209, v209
	v_exp_f32_e32 v210, v210
	v_exp_f32_e32 v211, v211
	v_exp_f32_e32 v212, v212
	v_exp_f32_e32 v213, v213
	v_exp_f32_e32 v214, v214
	v_exp_f32_e32 v215, v215
	s_waitcnt lgkmcnt(4)
	v_mfma_f32_32x32x16_bf16 v[34:49], v[126:129], v[66:69], v[34:49]
	v_exp_f32_e32 v216, v216
	v_exp_f32_e32 v217, v217
	v_exp_f32_e32 v218, v218
	v_exp_f32_e32 v219, v219
	s_waitcnt lgkmcnt(0)
	v_mfma_f32_32x32x16_bf16 v[50:65], v[106:109], v[66:69], v[50:65]
	v_exp_f32_e32 v220, v220
	v_exp_f32_e32 v221, v221
	v_exp_f32_e32 v222, v222
	v_exp_f32_e32 v223, v223
	v_mfma_f32_32x32x16_bf16 v[34:49], v[98:101], v[70:73], v[34:49]
	v_exp_f32_e32 v224, v224
	v_exp_f32_e32 v225, v225
	v_exp_f32_e32 v226, v226
	v_exp_f32_e32 v227, v227
	v_mfma_f32_32x32x16_bf16 v[50:65], v[102:105], v[70:73], v[50:65]
	v_exp_f32_e32 v228, v228
	v_exp_f32_e32 v229, v229
	v_exp_f32_e32 v230, v230
	v_exp_f32_e32 v231, v231
	v_mfma_f32_32x32x16_bf16 v[34:49], v[86:89], v[74:77], v[34:49]
	v_exp_f32_e32 v244, v244
	v_exp_f32_e32 v245, v245
	v_exp_f32_e32 v246, v246
	v_exp_f32_e32 v247, v247
	v_mfma_f32_32x32x16_bf16 v[50:65], v[94:97], v[74:77], v[50:65]
	v_exp_f32_e32 v248, v248
	v_exp_f32_e32 v249, v249
	v_exp_f32_e32 v250, v250
	v_exp_f32_e32 v251, v251
	v_mfma_f32_32x32x16_bf16 v[34:49], v[82:85], v[78:81], v[34:49]
	v_add_f32_e32 v196, v208, v209
	v_add_f32_e32 v197, v210, v211
	v_add_f32_e32 v198, v212, v213
	v_add_f32_e32 v199, v214, v215
	v_add_f32_e32 v196, v216, v196
	v_add_f32_e32 v197, v217, v197
	v_add_f32_e32 v198, v218, v198
	v_add_f32_e32 v199, v219, v199
	v_add_f32_e32 v196, v220, v196
	v_add_f32_e32 v197, v221, v197
	v_mfma_f32_32x32x16_bf16 v[50:65], v[90:93], v[78:81], v[50:65]
	v_add_f32_e32 v198, v222, v198
	v_add_f32_e32 v199, v223, v199
	v_add_f32_e32 v196, v224, v196
	v_add_f32_e32 v197, v225, v197
	v_add_f32_e32 v198, v226, v198
	v_add_f32_e32 v199, v227, v199
	v_add_f32_e32 v196, v228, v196
	v_add_f32_e32 v197, v229, v197
	v_add_f32_e32 v198, v230, v198
	v_add_f32_e32 v199, v231, v199
	v_add_f32_e32 v196, v244, v196
	v_add_f32_e32 v197, v245, v197
	v_add_f32_e32 v198, v246, v198
	v_add_f32_e32 v199, v247, v199
	v_add_f32_e32 v196, v248, v196
	v_add_f32_e32 v197, v249, v197
	v_add_f32_e32 v198, v250, v198
	v_add_f32_e32 v199, v251, v199
	v_add_f32_e32 v196, v196, v197
	v_add_f32_e32 v198, v198, v199
	v_add_f32_e32 v162, v196, v198
	v_cmp_neq_f32_e32 vcc, 1.0, v164
	s_cbranch_vccz .Lfx_norescale
	v_pk_mul_f32 v[32:33], v[32:33], v[164:165] op_sel_hi:[1,0]
	v_pk_mul_f32 v[30:31], v[30:31], v[164:165] op_sel_hi:[1,0]
	v_pk_mul_f32 v[28:29], v[28:29], v[164:165] op_sel_hi:[1,0]
	v_pk_mul_f32 v[26:27], v[26:27], v[164:165] op_sel_hi:[1,0]
	v_pk_mul_f32 v[24:25], v[24:25], v[164:165] op_sel_hi:[1,0]
	v_pk_mul_f32 v[22:23], v[22:23], v[164:165] op_sel_hi:[1,0]
	v_pk_mul_f32 v[20:21], v[20:21], v[164:165] op_sel_hi:[1,0]
	v_pk_mul_f32 v[18:19], v[18:19], v[164:165] op_sel_hi:[1,0]
	v_pk_mul_f32 v[16:17], v[16:17], v[164:165] op_sel_hi:[1,0]
	v_pk_mul_f32 v[14:15], v[14:15], v[164:165] op_sel_hi:[1,0]
	v_pk_mul_f32 v[12:13], v[12:13], v[164:165] op_sel_hi:[1,0]
	v_pk_mul_f32 v[10:11], v[10:11], v[164:165] op_sel_hi:[1,0]
	v_pk_mul_f32 v[8:9], v[8:9], v[164:165] op_sel_hi:[1,0]
	v_pk_mul_f32 v[6:7], v[6:7], v[164:165] op_sel_hi:[1,0]
	v_pk_mul_f32 v[4:5], v[4:5], v[164:165] op_sel_hi:[1,0]
	v_pk_mul_f32 v[2:3], v[2:3], v[164:165] op_sel_hi:[1,0]
.Lfx_norescale:
	v_fma_f32 v206, v206, v164, v162
	v_cvt_pk_bf16_f32 v122, v208, v209
	v_cvt_pk_bf16_f32 v123, v210, v211
	v_cvt_pk_bf16_f32 v124, v212, v213
	v_cvt_pk_bf16_f32 v125, v214, v215
	v_cvt_pk_bf16_f32 v118, v216, v217
	v_cvt_pk_bf16_f32 v119, v218, v219
	v_cvt_pk_bf16_f32 v120, v220, v221
	v_cvt_pk_bf16_f32 v121, v222, v223
	v_cvt_pk_bf16_f32 v114, v224, v225
	v_cvt_pk_bf16_f32 v115, v226, v227
	v_cvt_pk_bf16_f32 v116, v228, v229
	v_cvt_pk_bf16_f32 v117, v230, v231
	v_cvt_pk_bf16_f32 v110, v244, v245
	v_cvt_pk_bf16_f32 v111, v246, v247
	v_cvt_pk_bf16_f32 v112, v248, v249
	v_cvt_pk_bf16_f32 v113, v250, v251
	s_branch .LBB0_189
